# global attention loop: K/V addresses via per-wave SGPR bases + constant lane offsets (SALU adds) instead of 64-bit VALU pointer math
# speedup vs baseline: 1.0128x; 1.0077x over previous
; DI void attn_item(const Params& p, int layer, int item, char* smem) {
;   const int tid = tidx(), lane = tid & 63, wid = tid >> 6, l32 = lane & 31, h = lane >> 5;
;   int mode, b, hh, qb;
;   if (item < NAT_C) { mode = 0; b = item / 96; int rem = item % 96; hh = rem >> 4; qb = rem & 15; }
;   else if (item < NAT_C + NAT_B) { int it = item - NAT_C; mode = 1; b = it >> 6; hh = (it & 63) >> 4; qb = it & 15; }
;   else if (item < NAT_LAT) { int it = item - NAT_C - NAT_B; mode = 2; b = it / 96; int rem = it % 96; hh = rem >> 4; qb = rem & 15; }
;   else { int it = item - NAT_LAT; mode = 3; b = it >> 4; hh = it & 15; qb = 0; }
;   int qchunk, kchunk, vchunk, head16, t0 = 0, t1 = 0, qpos0 = qb * 256;
;   bool hasSink = false; float sinkv = 0.f;
;   int maskmode = 0;
;   if (mode == 0) { qchunk = 22 + hh; kchunk = 28 + hh / 3; vchunk = 30 + hh / 3; head16 = 10 + hh; t0 = 0; t1 = 64; }
;   else if (mode == 1) {
;     qchunk = 10 + hh; kchunk = 14 + hh; vchunk = 18 + hh; head16 = 6 + hh; maskmode = 1;
;     t0 = min(max(4 * qb - 4, 0), 56); t1 = min(max(4 * qb + 3 - 4, 0), 56) + 8;
;   } else if (mode == 2) {
;     qchunk = hh; kchunk = 6 + hh / 3; vchunk = 8 + hh / 3; head16 = hh; maskmode = 2;
;     t0 = max(0, 4 * qb - 2); t1 = min(64, 4 * qb + 6); hasSink = true; sinkv = p.sink[layer * 6 + hh];
;   } else {
;     head16 = hh; qpos0 = 4096;
;     if (hh < 6) { qchunk = hh; kchunk = 6 + hh / 3; vchunk = 8 + hh / 3; hasSink = true; sinkv = p.sink[layer * 6 + hh]; }
;     else if (hh < 10) { int hb = hh - 6; qchunk = 10 + hb; kchunk = 14 + hb; vchunk = 18 + hb; }
;     else { int hc = hh - 10; qchunk = 22 + hc; kchunk = 28 + hc / 3; vchunk = 30 + hc / 3; }
;   }
;   const int n_it = 4 + (t1 - t0);
;   const u16* Qb = p.QKV + (size_t)(b * 32 + qchunk) * LTOT * 64;
;   const u16* Kb = p.QKV + (size_t)(b * 32 + kchunk) * LTOT * 64;
;   const u16* Vb = p.QKV + (size_t)(b * 32 + vchunk) * LTOT * 64;
;   float* s_rpb = (float*)(smem + RPB_OFF);
;   if (mode == 1) {
;     const float* rp = p.rpb + (size_t)(layer * 4 + hh) * 465;
;     for (int e = tid; e < 465; e += NTHR) s_rpb[e] = rp[e] * LOG2E;
;   }
;   const int qpos = qpos0 + wid * 32 + l32;
;   bf16x8 qf[4];
; #pragma unroll
;   for (int s = 0; s < 4; ++s) qf[s] = *(const bf16x8*)(Qb + (size_t)qpos * 64 + s * 16 + h * 8);
;   f32x16 o0, o1;
; #pragma unroll
.LBB0_259:
	s_mul_hi_i32 s0, s14, 0x2aaaaaab
	s_lshr_b32 s1, s0, 31
	s_ashr_i32 s5, s0, 4
	s_add_i32 s5, s5, s1
	s_mul_i32 s0, s5, 0x60
	s_sub_i32 s0, s14, s0
	v_mov_b32_e32 v32, v213
	s_ashr_i32 s4, s0, 4
	s_lshl_b32 s0, s0, 8
	s_and_b32 s8, s0, 0xf00
	s_lshl_b32 s0, s5, 5
	v_ashrrev_i32_e32 v0, 1, v32
	s_add_i32 s1, s4, s0
	s_mul_i32 s2, s4, 0x56
	v_and_b32_e32 v0, 0xffffffe0, v0
	v_and_b32_e32 v36, 31, v32
	s_bfe_u32 s3, s2, 0x1000f
	s_bfe_u32 s2, s2, 0x80008
	s_add_i32 s1, s1, 22
	v_add_u32_e32 v0, s8, v0
	s_add_i32 s2, s2, s3
	s_mul_hi_i32 s3, s1, 0x88000
	s_mul_i32 s1, s1, 0x88000
	v_or_b32_e32 v134, v0, v36
	s_add_u32 s6, s88, s1
	v_ashrrev_i32_e32 v135, 31, v134
	v_bfe_u32 v140, v32, 5, 1
	s_addc_u32 s7, s89, s3
	v_lshlrev_b64 v[2:3], 7, v[134:135]
	v_lshl_add_u64 v[2:3], s[6:7], 0, v[2:3]
	v_lshlrev_b32_e32 v18, 4, v140
	v_mov_b32_e32 v19, v1
	v_readlane_b32 s6, v254, 50
	v_lshl_add_u64 v[2:3], v[2:3], 0, v[18:19]
	v_readlane_b32 s7, v254, 51
	global_load_dwordx4 v[98:101], v[2:3], off
	global_load_dwordx4 v[102:105], v[2:3], off offset:32
	global_load_dwordx4 v[106:109], v[2:3], off offset:64
	global_load_dwordx4 v[110:113], v[2:3], off offset:96
	s_sext_i32_i8 s2, s2
	global_load_dword v2, v1, s[6:7] offset:8
	s_add_i32 s2, s0, s2
	s_mul_i32 s3, s2, 0x88000
	s_add_i32 s0, s2, 28
	s_mul_hi_i32 s1, s0, 0x88000
	s_add_i32 s0, s3, 0xee0000
	v_ashrrev_i32_e32 v30, 3, v32
	s_add_u32 s0, s88, s0
	v_ashrrev_i32_e32 v31, 31, v30
	s_addc_u32 s1, s89, s1
	v_lshlrev_b32_e32 v19, 4, v32
	v_lshlrev_b64 v[20:21], 7, v[30:31]
	v_lshl_add_u64 v[136:137], s[0:1], 0, v[20:21]
	s_mov_b32 s6, 0x80000
	s_add_i32 s2, s2, 30
	s_add_i32 s3, s3, 0xff0000
	s_mul_hi_i32 s9, s2, 0x88000
	s_add_u32 s2, s88, s3
	s_addc_u32 s3, s89, s9
	v_mov_b64_e32 v[26:27], s[2:3]
	v_mad_i64_i32 v[138:139], s[2:3], v30, s28, v[26:27]
	s_movk_i32 s3, 0x90
	s_mov_b32 s2, 0x82000
	v_mul_lo_u32 v30, v30, s3
	v_add_u32_e32 v30, 16, v30
	v_add_u32_e32 v144, 16, v18
	v_mul_u32_u24_e32 v145, 0x90, v36
	v_mad_u32_u24 v146, v36, s3, v144
	v_and_b32_e32 v0, 0x70, v19
	v_lshl_add_u64 v[34:35], v[136:137], 0, v[0:1]
	v_add_co_u32_e32 v22, vcc, s6, v34
	v_add_u32_e32 v135, v30, v0
	s_nop 0
	v_addc_co_u32_e32 v23, vcc, 0, v35, vcc
	global_load_dwordx4 v[22:25], v[22:23], off
	v_add_co_u32_e32 v26, vcc, s2, v34
	v_lshl_add_u64 v[74:75], v[138:139], 0, v[0:1]
	s_nop 0
	v_addc_co_u32_e32 v27, vcc, 0, v35, vcc
	global_load_dwordx4 v[26:29], v[26:27], off
	s_movk_i32 s2, 0x2000
	v_lshlrev_b32_e32 v78, 3, v32
	v_and_b32_e32 v78, 8, v78
	v_and_or_b32 v19, v19, s74, v78
	v_add_co_u32_e32 v78, vcc, s2, v74
	v_add_u32_e32 v19, v30, v19
	s_nop 0
	v_addc_co_u32_e32 v79, vcc, 0, v75, vcc
	global_load_dwordx4 v[30:33], v[78:79], off
	s_mov_b32 s2, 0x84000
	v_add_co_u32_e32 v80, vcc, s2, v34
	v_add_u32_e32 v141, 0x2000, v19
	s_nop 0
	v_addc_co_u32_e32 v81, vcc, 0, v35, vcc
	global_load_dwordx4 v[66:69], v[80:81], off
	global_load_dwordx4 v[70:73], v[78:79], off offset:256
	v_lshl_add_u64 v[80:81], s[0:1], 0, v[0:1]
	v_lshl_add_u64 v[76:77], v[80:81], 0, v[20:21]
	s_mov_b32 s0, 0x86000
	v_add_u32_e32 v143, 0x6800, v19
	s_waitcnt vmcnt(5)
	v_xor_b32_e32 v2, 0x80000000, v2
	v_mov_b32_e32 v3, v2
	v_mov_b32_e32 v4, v2
	v_mov_b32_e32 v5, v2
	v_mov_b32_e32 v6, v2
	v_mov_b32_e32 v7, v2
	v_mov_b32_e32 v8, v2
	v_mov_b32_e32 v9, v2
	v_mov_b32_e32 v10, v2
	v_mov_b32_e32 v11, v2
	v_mov_b32_e32 v12, v2
	v_mov_b32_e32 v13, v2
	v_mov_b32_e32 v14, v2
	v_mov_b32_e32 v15, v2
	v_mov_b32_e32 v16, v2
	v_mov_b32_e32 v17, v2
	s_waitcnt vmcnt(4)
	ds_write_b128 v135, v[22:25]
	s_waitcnt vmcnt(2)
	ds_write2_b64 v141, v[30:31], v[32:33] offset0:128 offset1:130
	v_mad_u32_u24 v30, v36, s3, 16
	v_add_u32_e32 v142, v30, v18
	global_load_dwordx4 v[30:33], v[78:79], off offset:128
	v_add_co_u32_e32 v18, vcc, s0, v76
	s_waitcnt lgkmcnt(0)
	s_barrier
	ds_write_b128 v135, v[26:29] offset:18432
	v_addc_co_u32_e32 v19, vcc, 0, v77, vcc
	s_waitcnt vmcnt(0)
	ds_write2_b64 v143, v[30:31], v[32:33] offset0:128 offset1:130
	global_load_dwordx4 v[114:117], v[18:19], off
	global_load_dwordx4 v[118:121], v[78:79], off offset:384
	ds_read_b128 v[34:37], v146
	ds_read_b128 v[38:41], v146 offset:32
	v_mov_b64_e32 v[132:133], s[94:95]
	v_mov_b64_e32 v[130:131], s[92:93]
	s_waitcnt lgkmcnt(1)
	v_mfma_f32_32x32x16_bf16 v[18:33], v[34:37], v[98:101], v[2:17]
	ds_read_b128 v[34:37], v146 offset:64
	ds_read_b128 v[50:53], v146 offset:4608
	s_waitcnt lgkmcnt(2)
	v_mfma_f32_32x32x16_bf16 v[18:33], v[38:41], v[102:105], v[18:33]
	s_waitcnt lgkmcnt(1)
	v_mfma_f32_32x32x16_bf16 v[18:33], v[34:37], v[106:109], v[18:33]
	ds_read_b128 v[34:37], v146 offset:96
	s_waitcnt lgkmcnt(0)
	v_mfma_f32_32x32x16_bf16 v[18:33], v[34:37], v[110:113], v[18:33]
	v_mfma_f32_32x32x16_bf16 v[34:49], v[50:53], v[98:101], v[2:17]
	ds_read_b128 v[50:53], v146 offset:4640
	s_nop 9
	v_exp_f32_e32 v18, v18
	v_exp_f32_e32 v19, v19
	v_exp_f32_e32 v20, v20
	v_exp_f32_e32 v21, v21
	v_exp_f32_e32 v22, v22
	v_exp_f32_e32 v23, v23
	s_waitcnt lgkmcnt(0)
	v_mfma_f32_32x32x16_bf16 v[34:49], v[50:53], v[102:105], v[34:49]
	ds_read_b128 v[50:53], v146 offset:4672
	v_exp_f32_e32 v24, v24
	v_exp_f32_e32 v25, v25
	v_cvt_pk_bf16_f32 v18, v18, v19
	v_cvt_pk_bf16_f32 v19, v20, v21
	v_cvt_pk_bf16_f32 v20, v22, v23
	v_cvt_pk_bf16_f32 v21, v24, v25
	s_waitcnt lgkmcnt(0)
	v_mfma_f32_32x32x16_bf16 v[34:49], v[50:53], v[106:109], v[34:49]
	ds_read_b128 v[50:53], v146 offset:4704
	ds_read_b128 v[22:25], v142 offset:9216
	ds_read_b128 v[78:81], v142 offset:9248
	v_exp_f32_e32 v82, v26
	v_exp_f32_e32 v83, v27
	v_exp_f32_e32 v84, v28
	v_exp_f32_e32 v85, v29
	v_exp_f32_e32 v122, v30
	s_waitcnt lgkmcnt(2)
; DI void attn_item(const Params& p, int layer, int item, char* smem) {
;     ...
;       const char* sK = smem + bufsel * KV_B;
;       const char* sV = sK + KT_B;
;       f32x16 S[2];
; #pragma unroll
;       for (int kt = 0; kt < 2; ++kt) {
; #pragma unroll
;         for (int s = 0; s < 4; ++s) {
;           bf16x8 kf = *(const bf16x8*)(sK + (kt * 32 + l32) * KROW + s * 32 + h * 16);
;           S[kt] = MFMA32(kf, qf[s], s == 0 ? cinit : S[kt]);
;         }
;       }
;       if (tile < 64 && maskmode == 1) {
;         int qr = tq >> 6, qc = tq & 63;
;         int ws = min(max(qc - 8, 0), 48);
;         int dr = tile - qr + 7;
; #pragma unroll
;         for (int kt = 0; kt < 2; ++kt)
; #pragma unroll
;           for (int r = 0; r < 16; ++r) {
;             int kc = kt * 32 + crow(r, h);
;             bool ok = (unsigned)(kc - ws) < 16u;
;             int bi = ok ? (dr * 31 + kc - qc + 15) : 0;
;             float bv = s_rpb[bi];
;             S[kt][r] = ok ? (S[kt][r] + bv) : -INFINITY;
;           }
;       } else if (tile < 64 && maskmode == 2) {
; #pragma unroll
;         for (int kt = 0; kt < 2; ++kt)
; #pragma unroll
;           for (int r = 0; r < 16; ++r) {
;             int tk = tile * 64 + kt * 32 + crow(r, h);
;             int dd = tq - tk;
;             bool ok = (dd <= 128) && (dd >= -128);
;             S[kt][r] = ok ? S[kt][r] : -INFINITY;
;           }
;       }
; #pragma unroll
;       for (int r = 0; r < 16; ++r) {
;         S[0][r] = __builtin_amdgcn_exp2f(S[0][r]);
;         S[1][r] = __builtin_amdgcn_exp2f(S[1][r]);
;       }
; #pragma unroll
;       for (int kt = 0; kt < 2; ++kt)
; #pragma unroll
;         for (int s2 = 0; s2 < 2; ++s2) {
;           uint4 pw;
;           pw.x = pack_bf16(S[kt][8 * s2 + 0], S[kt][8 * s2 + 1]);
;           pw.y = pack_bf16(S[kt][8 * s2 + 2], S[kt][8 * s2 + 3]);
;           pw.z = pack_bf16(S[kt][8 * s2 + 4], S[kt][8 * s2 + 5]);
;           pw.w = pack_bf16(S[kt][8 * s2 + 6], S[kt][8 * s2 + 7]);
;           bf16x8 pf = __builtin_bit_cast(bf16x8, pw);
;           const int koff = (kt * 32 + 16 * s2 + 8 * h) * 2;
;           {
;             bf16x8 vf = *(const bf16x8*)(sV + l32 * VROW + koff);
;             o0 = MFMA32(vf, pf, o0);
;             lacc = MFMA32(ones, pf, lacc);
;           }
;           {
;             bf16x8 vf = *(const bf16x8*)(sV + (32 + l32) * VROW + koff);
	v_mfma_f32_32x32x16_bf16 v[34:49], v[50:53], v[110:113], v[34:49]
	v_exp_f32_e32 v124, v31
	v_exp_f32_e32 v126, v32
	v_exp_f32_e32 v128, v33
	v_cvt_pk_bf16_f32 v82, v82, v83
	v_cvt_pk_bf16_f32 v83, v84, v85
	v_cvt_pk_bf16_f32 v84, v122, v124
	v_cvt_pk_bf16_f32 v85, v126, v128
	s_nop 4
	v_exp_f32_e32 v86, v34
	v_exp_f32_e32 v87, v35
	v_exp_f32_e32 v88, v36
	v_exp_f32_e32 v89, v37
	v_exp_f32_e32 v90, v38
	v_exp_f32_e32 v91, v39
	v_exp_f32_e32 v92, v40
	v_exp_f32_e32 v93, v41
	v_exp_f32_e32 v94, v42
	v_exp_f32_e32 v95, v43
	v_exp_f32_e32 v96, v44
	v_exp_f32_e32 v97, v45
	v_exp_f32_e32 v123, v46
	v_exp_f32_e32 v125, v47
	v_exp_f32_e32 v127, v48
	v_exp_f32_e32 v129, v49
	s_waitcnt lgkmcnt(1)
	v_mfma_f32_32x32x16_bf16 v[34:49], v[22:25], v[18:21], 0
	ds_read_b128 v[22:25], v142 offset:13824
	s_waitcnt lgkmcnt(1)
	v_mfma_f32_32x32x16_bf16 v[34:49], v[78:81], v[82:85], v[34:49]
	ds_read_b128 v[78:81], v142 offset:13856
	v_mfma_f32_32x32x16_bf16 v[50:65], v[130:133], v[18:21], 0
	s_waitcnt lgkmcnt(1)
	v_mfma_f32_32x32x16_bf16 v[18:33], v[22:25], v[18:21], 0
	v_mfma_f32_32x32x16_bf16 v[50:65], v[130:133], v[82:85], v[50:65]
	s_waitcnt lgkmcnt(0)
	v_mfma_f32_32x32x16_bf16 v[18:33], v[78:81], v[82:85], v[18:33]
	ds_read_b128 v[82:85], v142 offset:9280
	v_cvt_pk_bf16_f32 v78, v86, v87
	v_cvt_pk_bf16_f32 v79, v88, v89
	v_cvt_pk_bf16_f32 v80, v90, v91
	v_cvt_pk_bf16_f32 v81, v92, v93
	s_waitcnt lgkmcnt(0)
	s_nop 0
	v_mfma_f32_32x32x16_bf16 v[34:49], v[82:85], v[78:81], v[34:49]
	ds_read_b128 v[82:85], v142 offset:13888
	s_waitcnt lgkmcnt(0)
	v_mfma_f32_32x32x16_bf16 v[18:33], v[82:85], v[78:81], v[18:33]
	ds_read_b128 v[82:85], v142 offset:9312
	v_mfma_f32_32x32x16_bf16 v[50:65], v[130:133], v[78:81], v[50:65]
	v_cvt_pk_bf16_f32 v78, v94, v95
	v_cvt_pk_bf16_f32 v79, v96, v97
	v_cvt_pk_bf16_f32 v80, v123, v125
	v_cvt_pk_bf16_f32 v81, v127, v129
	s_waitcnt lgkmcnt(0)
	s_nop 0
	v_mfma_f32_32x32x16_bf16 v[34:49], v[82:85], v[78:81], v[34:49]
	ds_read_b128 v[82:85], v142 offset:13920
	s_waitcnt lgkmcnt(0)
	s_barrier
	ds_write_b128 v135, v[66:69]
	ds_write2_b64 v141, v[70:71], v[72:73] offset0:128 offset1:130
	global_load_dwordx4 v[122:125], v[76:77], off
	global_load_dwordx4 v[126:129], v[74:75], off
	v_mfma_f32_32x32x16_bf16 v[50:65], v[130:133], v[78:81], v[50:65]
	v_mfma_f32_32x32x16_bf16 v[18:33], v[82:85], v[78:81], v[18:33]
	ds_read_b128 v[82:85], v146 offset:18432
	ds_read_b128 v[86:89], v146 offset:18464
	s_mov_b32 s2, 2
	v_add_u32_e32 v144, v144, v145
	s_waitcnt lgkmcnt(1)
	v_mfma_f32_32x32x16_bf16 v[66:81], v[82:85], v[98:101], v[2:17]
	ds_read_b128 v[82:85], v146 offset:18496
	ds_read_b128 v[148:151], v146 offset:23040
	s_waitcnt lgkmcnt(2)
	v_mfma_f32_32x32x16_bf16 v[66:81], v[86:89], v[102:105], v[66:81]
	s_waitcnt lgkmcnt(1)
	v_mfma_f32_32x32x16_bf16 v[66:81], v[82:85], v[106:109], v[66:81]
	ds_read_b128 v[82:85], v146 offset:18528
	s_waitcnt lgkmcnt(0)
	v_mfma_f32_32x32x16_bf16 v[66:81], v[82:85], v[110:113], v[66:81]
	v_mfma_f32_32x32x16_bf16 v[82:97], v[148:151], v[98:101], v[2:17]
	ds_read_b128 v[148:151], v146 offset:23072
	s_nop 9
	v_exp_f32_e32 v66, v66
	v_exp_f32_e32 v67, v67
	v_exp_f32_e32 v68, v68
	v_exp_f32_e32 v69, v69
	v_exp_f32_e32 v70, v70
	v_exp_f32_e32 v71, v71
	s_waitcnt lgkmcnt(0)
	v_mfma_f32_32x32x16_bf16 v[82:97], v[148:151], v[102:105], v[82:97]
	ds_read_b128 v[148:151], v146 offset:23104
	v_exp_f32_e32 v72, v72
	v_exp_f32_e32 v73, v73
	v_cvt_pk_bf16_f32 v66, v66, v67
	v_cvt_pk_bf16_f32 v67, v68, v69
	v_cvt_pk_bf16_f32 v68, v70, v71
	v_cvt_pk_bf16_f32 v69, v72, v73
	s_waitcnt lgkmcnt(0)
	v_mfma_f32_32x32x16_bf16 v[82:97], v[148:151], v[106:109], v[82:97]
	ds_read_b128 v[146:149], v146 offset:23136
	v_exp_f32_e32 v78, v78
	v_exp_f32_e32 v79, v79
	v_exp_f32_e32 v80, v80
	v_exp_f32_e32 v81, v81
	s_waitcnt lgkmcnt(0)
	v_mfma_f32_32x32x16_bf16 v[82:97], v[146:149], v[110:113], v[82:97]
	v_exp_f32_e32 v146, v74
	v_exp_f32_e32 v147, v75
	v_exp_f32_e32 v148, v76
	v_exp_f32_e32 v149, v77
	ds_read_b128 v[70:73], v142 offset:27648
	ds_read_b128 v[74:77], v142 offset:27680
	s_nop 5
	v_exp_f32_e32 v82, v82
	s_waitcnt lgkmcnt(1)
	v_mfma_f32_32x32x16_bf16 v[34:49], v[70:73], v[66:69], v[34:49]
	ds_read_b128 v[70:73], v142 offset:32256
	v_exp_f32_e32 v83, v83
	v_exp_f32_e32 v84, v84
	v_exp_f32_e32 v85, v85
	v_exp_f32_e32 v86, v86
	v_exp_f32_e32 v87, v87
	v_exp_f32_e32 v88, v88
	s_waitcnt lgkmcnt(0)
	v_mfma_f32_32x32x16_bf16 v[18:33], v[70:73], v[66:69], v[18:33]
	ds_read_b128 v[70:73], v142 offset:32288
	v_exp_f32_e32 v89, v89
	v_exp_f32_e32 v90, v90
	v_exp_f32_e32 v91, v91
	v_exp_f32_e32 v92, v92
	v_exp_f32_e32 v93, v93
	v_exp_f32_e32 v94, v94
	v_mfma_f32_32x32x16_bf16 v[50:65], v[130:133], v[66:69], v[50:65]
	v_cvt_pk_bf16_f32 v66, v146, v147
	v_cvt_pk_bf16_f32 v67, v148, v149
	v_cvt_pk_bf16_f32 v68, v78, v79
	v_cvt_pk_bf16_f32 v69, v80, v81
	v_exp_f32_e32 v95, v95
	v_exp_f32_e32 v96, v96
	v_exp_f32_e32 v97, v97
	s_waitcnt lgkmcnt(0)
	v_mfma_f32_32x32x16_bf16 v[18:33], v[70:73], v[66:69], v[18:33]
	ds_read_b128 v[70:73], v142 offset:27712
	v_mfma_f32_32x32x16_bf16 v[34:49], v[74:77], v[66:69], v[34:49]
	v_mfma_f32_32x32x16_bf16 v[50:65], v[130:133], v[66:69], v[50:65]
	v_cvt_pk_bf16_f32 v66, v82, v83
	v_cvt_pk_bf16_f32 v67, v84, v85
	v_cvt_pk_bf16_f32 v68, v86, v87
	v_cvt_pk_bf16_f32 v69, v88, v89
	s_waitcnt lgkmcnt(0)
	s_nop 0
	v_mfma_f32_32x32x16_bf16 v[34:49], v[70:73], v[66:69], v[34:49]
	ds_read_b128 v[70:73], v142 offset:32320
	s_waitcnt lgkmcnt(0)
	v_mfma_f32_32x32x16_bf16 v[18:33], v[70:73], v[66:69], v[18:33]
	ds_read_b128 v[70:73], v142 offset:27744
	v_mfma_f32_32x32x16_bf16 v[50:65], v[130:133], v[66:69], v[50:65]
	v_cvt_pk_bf16_f32 v66, v90, v91
	v_cvt_pk_bf16_f32 v67, v92, v93
	v_cvt_pk_bf16_f32 v68, v94, v95
	v_cvt_pk_bf16_f32 v69, v96, v97
	s_waitcnt lgkmcnt(0)
	s_nop 0
	v_mfma_f32_32x32x16_bf16 v[34:49], v[70:73], v[66:69], v[34:49]
	ds_read_b128 v[70:73], v142 offset:32352
	s_waitcnt lgkmcnt(0)
	s_barrier
	v_mfma_f32_32x32x16_bf16 v[50:65], v[130:133], v[66:69], v[50:65]
	v_mfma_f32_32x32x16_bf16 v[18:33], v[70:73], v[66:69], v[18:33]
	s_nop 11
	v_mov_b32_e32 v51, 0
	v_mov_b32_e32 v52, 0
	v_lshl_add_u64 v[132:133], v[136:137], 0, v[0:1]
	v_lshl_add_u64 v[130:131], v[138:139], 0, v[0:1]
	s_nop 0
	v_readfirstlane_b32 s92, v132
	v_readfirstlane_b32 s93, v133
	v_readfirstlane_b32 s94, v130
	v_readfirstlane_b32 s95, v131
	s_nop 3
	v_subrev_u32_e32 v53, s92, v132
	v_subrev_u32_e32 v54, s94, v130
	s_add_u32 s92, s92, 0x2000
	s_addc_u32 s93, s93, 0
	s_branch .LBB0_261
; DI void attn_item(const Params& p, int layer, int item, char* smem) {
;     ...
;       const char* sK = smem + bufsel * KV_B;
;       const char* sV = sK + KT_B;
;       f32x16 S[2];
; #pragma unroll
;       for (int kt = 0; kt < 2; ++kt) {
; #pragma unroll
;         for (int s = 0; s < 4; ++s) {
;           bf16x8 kf = *(const bf16x8*)(sK + (kt * 32 + l32) * KROW + s * 32 + h * 16);
;           S[kt] = MFMA32(kf, qf[s], s == 0 ? cinit : S[kt]);
;         }
;       }
;       if (tile < 64 && maskmode == 1) {
;         int qr = tq >> 6, qc = tq & 63;
;         int ws = min(max(qc - 8, 0), 48);
;         int dr = tile - qr + 7;
; #pragma unroll
;         for (int kt = 0; kt < 2; ++kt)
; #pragma unroll
;           for (int r = 0; r < 16; ++r) {
;             int kc = kt * 32 + crow(r, h);
;             bool ok = (unsigned)(kc - ws) < 16u;
;             int bi = ok ? (dr * 31 + kc - qc + 15) : 0;
;             float bv = s_rpb[bi];
;             S[kt][r] = ok ? (S[kt][r] + bv) : -INFINITY;
;           }
;       } else if (tile < 64 && maskmode == 2) {
; #pragma unroll
;         for (int kt = 0; kt < 2; ++kt)
; #pragma unroll
;           for (int r = 0; r < 16; ++r) {
;             int tk = tile * 64 + kt * 32 + crow(r, h);
;             int dd = tq - tk;
;             bool ok = (dd <= 128) && (dd >= -128);
;             S[kt][r] = ok ? S[kt][r] : -INFINITY;
;           }
;       }
; #pragma unroll
;       for (int r = 0; r < 16; ++r) {
;         S[0][r] = __builtin_amdgcn_exp2f(S[0][r]);
;         S[1][r] = __builtin_amdgcn_exp2f(S[1][r]);
;       }
; #pragma unroll
;       for (int kt = 0; kt < 2; ++kt)
; #pragma unroll
;         for (int s2 = 0; s2 < 2; ++s2) {
;           uint4 pw;
;           pw.x = pack_bf16(S[kt][8 * s2 + 0], S[kt][8 * s2 + 1]);
;           pw.y = pack_bf16(S[kt][8 * s2 + 2], S[kt][8 * s2 + 3]);
;           pw.z = pack_bf16(S[kt][8 * s2 + 4], S[kt][8 * s2 + 5]);
;           pw.w = pack_bf16(S[kt][8 * s2 + 6], S[kt][8 * s2 + 7]);
;           bf16x8 pf = __builtin_bit_cast(bf16x8, pw);
;           const int koff = (kt * 32 + 16 * s2 + 8 * h) * 2;
;           {
;     ...
;     if (it + 1 < n_it) {
;       if (it + 2 < n_it) { ASWRITE(ka0, va0, 0); }
;       if (it + 4 < n_it) { AGLOAD(ka0, va0, TILE_OF(it + 4)); }
;       __builtin_amdgcn_sched_barrier(0);
;       compute(1, TILE_OF(it + 1));
;       __syncthreads();
;     }
.LBB0_260:
	ds_read_b128 v[82:85], v144 offset:18432
	ds_read_b128 v[86:89], v144 offset:18464
	s_add_i32 s2, s2, 2
	s_add_u32 s92, s92, 0x2000
	s_addc_u32 s93, s93, 0
	s_add_u32 s94, s94, 0x100
	s_addc_u32 s95, s95, 0
	s_waitcnt lgkmcnt(1)
	v_mfma_f32_32x32x16_bf16 v[66:81], v[82:85], v[98:101], v[2:17]
	ds_read_b128 v[82:85], v144 offset:18496
	ds_read_b128 v[130:133], v144 offset:23040
	s_andn2_b64 vcc, exec, s[0:1]
	s_waitcnt lgkmcnt(2)
	v_mfma_f32_32x32x16_bf16 v[66:81], v[86:89], v[102:105], v[66:81]
	s_waitcnt lgkmcnt(1)
	v_mfma_f32_32x32x16_bf16 v[66:81], v[82:85], v[106:109], v[66:81]
	ds_read_b128 v[82:85], v144 offset:18528
	s_waitcnt lgkmcnt(0)
	v_mfma_f32_32x32x16_bf16 v[66:81], v[82:85], v[110:113], v[66:81]
	v_mfma_f32_32x32x16_bf16 v[82:97], v[130:133], v[98:101], v[2:17]
	ds_read_b128 v[130:133], v144 offset:23072
	s_nop 9
	v_exp_f32_e32 v66, v66
	v_exp_f32_e32 v67, v67
	v_exp_f32_e32 v68, v68
	v_exp_f32_e32 v69, v69
	v_exp_f32_e32 v70, v70
	v_exp_f32_e32 v71, v71
	s_waitcnt lgkmcnt(0)
	v_mfma_f32_32x32x16_bf16 v[82:97], v[130:133], v[102:105], v[82:97]
	ds_read_b128 v[130:133], v144 offset:23104
	v_exp_f32_e32 v72, v72
	v_exp_f32_e32 v73, v73
	v_add_f32_e32 v51, v51, v66
	v_add_f32_e32 v52, v52, v67
	v_add_f32_e32 v51, v51, v68
	v_add_f32_e32 v52, v52, v69
	v_cvt_pk_bf16_f32 v66, v66, v67
	v_cvt_pk_bf16_f32 v67, v68, v69
	s_waitcnt lgkmcnt(0)
	v_mfma_f32_32x32x16_bf16 v[82:97], v[130:133], v[106:109], v[82:97]
	ds_read_b128 v[130:133], v144 offset:23136
	v_add_f32_e32 v51, v51, v70
	v_add_f32_e32 v52, v52, v71
	v_cvt_pk_bf16_f32 v68, v70, v71
	v_add_f32_e32 v51, v51, v72
	v_add_f32_e32 v52, v52, v73
	v_cvt_pk_bf16_f32 v69, v72, v73
	v_exp_f32_e32 v145, v78
	v_exp_f32_e32 v146, v79
	s_waitcnt lgkmcnt(0)
	v_mfma_f32_32x32x16_bf16 v[82:97], v[130:133], v[110:113], v[82:97]
	v_exp_f32_e32 v147, v80
	v_exp_f32_e32 v148, v81
	v_exp_f32_e32 v130, v74
	v_exp_f32_e32 v131, v75
	v_exp_f32_e32 v132, v76
	v_exp_f32_e32 v133, v77
	ds_read_b128 v[70:73], v142 offset:27648
	ds_read_b128 v[74:77], v142 offset:27680
	ds_read_b128 v[78:81], v142 offset:32256
	v_add_f32_e32 v51, v51, v145
	v_add_f32_e32 v52, v52, v146
	v_add_f32_e32 v51, v51, v147
	v_add_f32_e32 v52, v52, v148
	v_exp_f32_e32 v82, v82
	s_waitcnt lgkmcnt(2)
	v_mfma_f32_32x32x16_bf16 v[34:49], v[70:73], v[66:69], v[34:49]
	v_exp_f32_e32 v83, v83
	v_exp_f32_e32 v84, v84
	v_exp_f32_e32 v85, v85
	v_add_f32_e32 v51, v51, v130
	v_add_f32_e32 v52, v52, v131
	v_add_f32_e32 v51, v51, v132
	v_add_f32_e32 v52, v52, v133
	v_exp_f32_e32 v86, v86
	v_exp_f32_e32 v87, v87
	v_exp_f32_e32 v88, v88
	v_exp_f32_e32 v89, v89
	s_waitcnt lgkmcnt(0)
	v_mfma_f32_32x32x16_bf16 v[18:33], v[78:81], v[66:69], v[18:33]
	v_cvt_pk_bf16_f32 v66, v130, v131
	v_cvt_pk_bf16_f32 v67, v132, v133
	v_cvt_pk_bf16_f32 v68, v145, v146
	v_cvt_pk_bf16_f32 v69, v147, v148
	v_exp_f32_e32 v90, v90
	v_exp_f32_e32 v91, v91
	v_exp_f32_e32 v92, v92
	v_mfma_f32_32x32x16_bf16 v[34:49], v[74:77], v[66:69], v[34:49]
	ds_read_b128 v[74:77], v142 offset:32288
	v_exp_f32_e32 v93, v93
	v_exp_f32_e32 v94, v94
	v_exp_f32_e32 v95, v95
	v_exp_f32_e32 v96, v96
	v_exp_f32_e32 v97, v97
	v_add_f32_e32 v51, v51, v82
	v_add_f32_e32 v52, v52, v83
	s_waitcnt lgkmcnt(0)
	v_mfma_f32_32x32x16_bf16 v[18:33], v[74:77], v[66:69], v[18:33]
	ds_read_b128 v[74:77], v142 offset:27712
	v_add_f32_e32 v51, v51, v84
	v_add_f32_e32 v52, v52, v85
	v_add_f32_e32 v51, v51, v86
	v_add_f32_e32 v52, v52, v87
	v_cvt_pk_bf16_f32 v66, v82, v83
	v_cvt_pk_bf16_f32 v67, v84, v85
	v_cvt_pk_bf16_f32 v68, v86, v87
	v_cvt_pk_bf16_f32 v69, v88, v89
	s_waitcnt lgkmcnt(0)
	s_nop 0
	v_mfma_f32_32x32x16_bf16 v[34:49], v[74:77], v[66:69], v[34:49]
	ds_read_b128 v[74:77], v142 offset:32320
	v_add_f32_e32 v51, v51, v88
	v_add_f32_e32 v52, v52, v89
	v_add_f32_e32 v51, v51, v90
	v_add_f32_e32 v52, v52, v91
	s_waitcnt lgkmcnt(0)
	v_mfma_f32_32x32x16_bf16 v[18:33], v[74:77], v[66:69], v[18:33]
	v_cvt_pk_bf16_f32 v66, v90, v91
	v_cvt_pk_bf16_f32 v67, v92, v93
	v_cvt_pk_bf16_f32 v68, v94, v95
	v_cvt_pk_bf16_f32 v69, v96, v97
	ds_read_b128 v[74:77], v142 offset:27744
	ds_read_b128 v[70:73], v142 offset:32352
	v_add_f32_e32 v51, v51, v92
	v_add_f32_e32 v52, v52, v93
	v_add_f32_e32 v51, v51, v94
	v_add_f32_e32 v52, v52, v95
	v_add_f32_e32 v51, v51, v96
	v_add_f32_e32 v52, v52, v97
	s_waitcnt lgkmcnt(0)
	s_barrier
	v_mfma_f32_32x32x16_bf16 v[34:49], v[74:77], v[66:69], v[34:49]
	v_mfma_f32_32x32x16_bf16 v[18:33], v[70:73], v[66:69], v[18:33]
	s_cbranch_vccz .LBB0_267
.LBB0_261:
	s_cmp_gt_u32 s2, 64
	s_waitcnt vmcnt(1)
	ds_write_b128 v135, v[114:117] offset:18432
	s_waitcnt vmcnt(0)
	ds_write2_b64 v143, v[118:119], v[120:121] offset0:128 offset1:130
	s_cbranch_scc1 .LBB0_263
	global_load_dwordx4 v[114:117], v53, s[92:93]
	global_load_dwordx4 v[118:121], v54, s[94:95] offset:128

; DI void attn_item(const Params& p, int layer, int item, char* smem) {
;     ...
;       if (it + 4 < n_it) { AGLOAD(ka0, va0, TILE_OF(it + 4)); }
;     ...
;   float l_tot = lacc[0];
;   if (hasSink) l_tot += __builtin_amdgcn_exp2f(sinkv * LOG2E - m_fix);
;   float inv = 1.f / l_tot;
;   int T = (mode == 3) ? (TLAT + b * 256 + (qpos - 4096)) : (b * 4096 + qpos);
;   u16* od = p.O + (size_t)T * LDK + head16 * 64;
; #pragma unroll
;   for (int g = 0; g < 4; ++g) {
;     int d0 = 8 * g + 4 * h;
;     *(uint2*)(od + d0) = make_uint2(pack_bf16(o0[4 * g] * inv, o0[4 * g + 1] * inv), pack_bf16(o0[4 * g + 2] * inv, o0[4 * g + 3] * inv));
;     *(uint2*)(od + 32 + d0) = make_uint2(pack_bf16(o1[4 * g] * inv, o1[4 * g + 1] * inv), pack_bf16(o1[4 * g + 2] * inv, o1[4 * g + 3] * inv));
;   }
.LBB0_265:
	s_add_u32 s92, s92, 0x2000
	s_addc_u32 s93, s93, 0
	s_cmp_gt_u32 s2, 63
	s_cbranch_scc1 .LBB0_260
	global_load_dwordx4 v[122:125], v53, s[92:93]
	global_load_dwordx4 v[126:129], v54, s[94:95] offset:256
	s_branch .LBB0_260
.LBB0_267:
	s_mov_b32 s92, 0x3f803f80
	s_mov_b32 s93, s92
	s_mov_b32 s94, s92
	s_mov_b32 s95, s92
	s_nop 5
	v_add_f32_e32 v51, v51, v52
	s_nop 0
	v_mov_b32_e32 v52, v51
	s_nop 1
	v_permlane32_swap_b32_e32 v51, v52
	s_nop 1
	v_add_f32_e32 v50, v50, v51
	v_add_f32_e32 v50, v50, v52
	v_div_scale_f32 v0, s[0:1], v50, v50, 1.0
	v_rcp_f32_e32 v3, v0
	v_lshl_add_u32 v2, s5, 12, v134
	s_lshl_b32 s0, s4, 6
	s_ashr_i32 s1, s0, 31
	v_fma_f32 v4, -v0, v3, 1.0
	v_fmac_f32_e32 v3, v4, v3
	v_div_scale_f32 v4, vcc, 1.0, v50, 1.0
	v_mul_f32_e32 v5, v4, v3
	v_fma_f32 v6, -v0, v5, v4
	v_fmac_f32_e32 v5, v6, v3
	v_fma_f32 v0, -v0, v5, v4
	v_div_fmas_f32 v0, v0, v3, v5
	v_ashrrev_i32_e32 v3, 31, v2
	v_lshlrev_b64 v[2:3], 11, v[2:3]
	v_div_fixup_f32 v4, v0, v50, 1.0
	v_lshl_add_u64 v[2:3], s[90:91], 0, v[2:3]
	v_lshl_add_u64 v[2:3], s[0:1], 1, v[2:3]
	v_lshlrev_b32_e32 v0, 4, v140
	v_lshl_add_u64 v[2:3], v[2:3], 0, v[0:1]
	v_pk_mul_f32 v[6:7], v[34:35], v[4:5] op_sel_hi:[1,0]
	v_pk_mul_f32 v[8:9], v[36:37], v[4:5] op_sel_hi:[1,0]
	v_pk_mul_f32 v[10:11], v[38:39], v[4:5] op_sel_hi:[1,0]
	v_pk_mul_f32 v[12:13], v[40:41], v[4:5] op_sel_hi:[1,0]
	v_cvt_pk_bf16_f32 v6, v6, v7
	v_cvt_pk_bf16_f32 v7, v8, v9
	v_cvt_pk_bf16_f32 v8, v10, v11
	v_cvt_pk_bf16_f32 v9, v12, v13
	s_nop 1
	v_permlane32_swap_b32_e32 v6, v8
	v_permlane32_swap_b32_e32 v7, v9
	global_store_dwordx4 v[2:3], v[6:9], off offset:1280
	v_pk_mul_f32 v[14:15], v[42:43], v[4:5] op_sel_hi:[1,0]
	v_pk_mul_f32 v[16:17], v[44:45], v[4:5] op_sel_hi:[1,0]
	v_pk_mul_f32 v[10:11], v[46:47], v[4:5] op_sel_hi:[1,0]
	v_pk_mul_f32 v[12:13], v[48:49], v[4:5] op_sel_hi:[1,0]
	v_cvt_pk_bf16_f32 v14, v14, v15
	v_cvt_pk_bf16_f32 v15, v16, v17
	v_cvt_pk_bf16_f32 v16, v10, v11
	v_cvt_pk_bf16_f32 v17, v12, v13
	s_nop 1
	v_permlane32_swap_b32_e32 v14, v16
	v_permlane32_swap_b32_e32 v15, v17
	global_store_dwordx4 v[2:3], v[14:17], off offset:1312
	v_pk_mul_f32 v[6:7], v[18:19], v[4:5] op_sel_hi:[1,0]
	v_pk_mul_f32 v[8:9], v[20:21], v[4:5] op_sel_hi:[1,0]
	v_pk_mul_f32 v[10:11], v[22:23], v[4:5] op_sel_hi:[1,0]
	v_pk_mul_f32 v[12:13], v[24:25], v[4:5] op_sel_hi:[1,0]
	v_cvt_pk_bf16_f32 v6, v6, v7
	v_cvt_pk_bf16_f32 v7, v8, v9
	v_cvt_pk_bf16_f32 v8, v10, v11
	v_cvt_pk_bf16_f32 v9, v12, v13
	s_nop 1
	v_permlane32_swap_b32_e32 v6, v8
	v_permlane32_swap_b32_e32 v7, v9
	global_store_dwordx4 v[2:3], v[6:9], off offset:1344
	v_pk_mul_f32 v[14:15], v[26:27], v[4:5] op_sel_hi:[1,0]
	v_pk_mul_f32 v[16:17], v[28:29], v[4:5] op_sel_hi:[1,0]
	v_pk_mul_f32 v[10:11], v[30:31], v[4:5] op_sel_hi:[1,0]
	v_pk_mul_f32 v[12:13], v[32:33], v[4:5] op_sel_hi:[1,0]
	v_cvt_pk_bf16_f32 v14, v14, v15
	v_cvt_pk_bf16_f32 v15, v16, v17
	v_cvt_pk_bf16_f32 v16, v10, v11
	v_cvt_pk_bf16_f32 v17, v12, v13
	s_nop 1
	v_permlane32_swap_b32_e32 v14, v16
	v_permlane32_swap_b32_e32 v15, v17
	global_store_dwordx4 v[2:3], v[14:17], off offset:1376
	s_and_saveexec_b64 s[0:1], s[68:69]
	s_cbranch_execz .LBB0_236
	s_branch .LBB0_498
